# static priority raise for waves 4-7 also during the sample item
# baseline (speedup 1.0000x reference)
.LBB0_289:
	s_or_b64 exec, exec, s[0:1]
	s_add_u32 s0, s24, 0x10000000
	s_addc_u32 s1, s25, 0
	v_writelane_b32 v247, s0, 21
	v_mov_b32_e32 v209, v222
	s_waitcnt lgkmcnt(0)
	v_writelane_b32 v247, s1, 22
	s_barrier
	v_writelane_b32 v247, s92, 23
	s_cmpk_lt_i32 s92, 0x100
	s_nop 0
	v_bfe_u32 v193, v209, 4, 2
	v_ashrrev_i32_e32 v112, 3, v209
	v_and_b32_e32 v189, 15, v209
	v_writelane_b32 v247, s93, 24
	s_mov_b32 s100, 0
	s_cbranch_scc0 .LBB0_394
	s_bitcmp1_b32 s92, 3
	s_cbranch_scc0 .Lstag_sample
	s_mov_b32 s100, 1
	s_branch .LBB0_394
.Lstag_sample:
	v_readfirstlane_b32 s98, v222
	s_cmp_ge_u32 s98, 0x100
	s_cbranch_scc0 .Lprio_samp
	s_setprio 1
.Lprio_samp:
	v_cmp_gt_i32_e64 s[0:1], 64, v209
	v_ashrrev_i32_e32 v101, 6, v209
	v_and_b32_e32 v0, 7, v209
	v_writelane_b32 v247, s0, 26
	v_and_b32_e32 v100, 63, v209
	v_lshlrev_b32_e32 v2, 3, v101
	v_writelane_b32 v247, s1, 27
	v_cmp_ge_i32_e64 s[0:1], v112, v0
	v_mov_b32_e32 v105, 0
	v_ashrrev_i32_e32 v3, 31, v2
	v_writelane_b32 v247, s0, 28
	v_lshlrev_b32_e32 v104, 2, v100
	v_lshlrev_b64 v[106:107], 6, v[2:3]
	v_writelane_b32 v247, s1, 29
	v_lshl_add_u64 v[2:3], s[22:23], 0, v[104:105]
	s_mov_b64 s[0:1], 0x4180000
	v_lshl_add_u64 v[110:111], v[2:3], 0, s[0:1]
	v_mbcnt_hi_u32_b32 v3, -1, v223
	v_and_b32_e32 v5, 64, v3
	v_add_u32_e32 v5, 64, v5
	v_xor_b32_e32 v6, 1, v3
	v_cmp_lt_i32_e32 vcc, v6, v5
	v_cmp_lt_i32_e64 s[0:1], -1, v101
	v_lshl_add_u32 v115, v112, 8, 0
	v_cndmask_b32_e32 v6, v3, v6, vcc
	v_lshlrev_b32_e32 v213, 2, v6
	v_xor_b32_e32 v6, 2, v3
	v_cmp_lt_i32_e32 vcc, v6, v5
	v_writelane_b32 v247, s0, 30
	v_lshl_add_u32 v114, v101, 5, 0
	v_cndmask_b32_e32 v6, v3, v6, vcc
	v_lshlrev_b32_e32 v214, 2, v6
	v_xor_b32_e32 v6, 4, v3
	v_cmp_lt_i32_e32 vcc, v6, v5
	v_and_b32_e32 v2, 0x3fffffc0, v209
	v_writelane_b32 v247, s1, 31
	v_cndmask_b32_e32 v6, v3, v6, vcc
	v_lshlrev_b32_e32 v215, 2, v6
	v_xor_b32_e32 v6, 8, v3
	v_cmp_lt_i32_e32 vcc, v6, v5
	s_movk_i32 s0, 0x6e0
	v_lshl_add_u32 v2, v2, 2, 0
	v_cndmask_b32_e32 v6, v3, v6, vcc
	v_lshlrev_b32_e32 v216, 2, v6
	v_xor_b32_e32 v6, 16, v3
	v_cmp_lt_i32_e32 vcc, v6, v5
	v_mad_u64_u32 v[118:119], s[0:1], v101, s0, v[114:115]
	s_nop 0
	v_cndmask_b32_e32 v6, v3, v6, vcc
	v_lshlrev_b32_e32 v217, 2, v6
	v_xor_b32_e32 v6, 32, v3
	v_cmp_lt_i32_e32 vcc, v6, v5
	v_add_u32_e32 v219, 0x800, v101
	v_add_u32_e32 v211, v2, v104
	v_cndmask_b32_e32 v3, v3, v6, vcc
	v_lshl_add_u32 v119, v189, 4, v2
	s_movk_i32 s33, 0x800
	v_sub_u32_e32 v2, v219, v193
	v_lshlrev_b32_e32 v218, 2, v3
	v_cmp_gt_i32_e64 s[0:1], s33, v2
	v_add_u32_e32 v28, 0xfffff800, v2
	v_ashrrev_i32_e32 v3, 31, v2
	v_or_b32_e32 v5, 4, v193
	v_cndmask_b32_e64 v3, 0, v3, s[0:1]
	v_writelane_b32 v247, s0, 32
	v_or_b32_e32 v6, 8, v193
	v_or_b32_e32 v7, 12, v193
	v_cndmask_b32_e64 v2, v28, v2, s[0:1]
	v_lshlrev_b64 v[120:121], 11, v[2:3]
	v_sub_u32_e32 v2, v219, v5
	v_writelane_b32 v247, s1, 33
	v_cmp_gt_i32_e64 s[0:1], s33, v2
	v_ashrrev_i32_e32 v3, 31, v2
	v_add_u32_e32 v5, 0xfffff800, v2
	v_cndmask_b32_e64 v3, 0, v3, s[0:1]
	v_writelane_b32 v247, s0, 34
	v_or_b32_e32 v8, 16, v193
	v_or_b32_e32 v9, 20, v193
	v_cndmask_b32_e64 v2, v5, v2, s[0:1]
	v_lshlrev_b64 v[122:123], 11, v[2:3]
	v_sub_u32_e32 v2, v219, v6
	v_writelane_b32 v247, s1, 35
	v_cmp_gt_i32_e64 s[0:1], s33, v2
	v_ashrrev_i32_e32 v3, 31, v2
	v_add_u32_e32 v5, 0xfffff800, v2
	v_cndmask_b32_e64 v3, 0, v3, s[0:1]
	v_writelane_b32 v247, s0, 36
	v_or_b32_e32 v10, 24, v193
	v_or_b32_e32 v11, 28, v193
	v_cndmask_b32_e64 v2, v5, v2, s[0:1]
	v_lshlrev_b64 v[124:125], 11, v[2:3]
	v_sub_u32_e32 v2, v219, v7
	v_writelane_b32 v247, s1, 37
	v_cmp_gt_i32_e64 s[0:1], s33, v2
	v_ashrrev_i32_e32 v3, 31, v2
	v_add_u32_e32 v5, 0xfffff800, v2
	v_cndmask_b32_e64 v3, 0, v3, s[0:1]
	v_writelane_b32 v247, s0, 38
	v_or_b32_e32 v12, 32, v193
	v_or_b32_e32 v13, 36, v193
	v_cndmask_b32_e64 v2, v5, v2, s[0:1]
	v_lshlrev_b64 v[126:127], 11, v[2:3]
	v_sub_u32_e32 v2, v219, v8
	v_writelane_b32 v247, s1, 39
	v_cmp_gt_i32_e64 s[0:1], s33, v2
	v_ashrrev_i32_e32 v3, 31, v2
	v_add_u32_e32 v5, 0xfffff800, v2
	v_cndmask_b32_e64 v3, 0, v3, s[0:1]
	v_writelane_b32 v247, s0, 40
	v_or_b32_e32 v14, 40, v193
	v_or_b32_e32 v15, 44, v193
	v_cndmask_b32_e64 v2, v5, v2, s[0:1]
	v_lshlrev_b64 v[128:129], 11, v[2:3]
	v_sub_u32_e32 v2, v219, v9
	v_cmp_gt_i32_e64 s[94:95], s33, v2
	v_ashrrev_i32_e32 v3, 31, v2
	v_add_u32_e32 v5, 0xfffff800, v2
	v_cndmask_b32_e64 v3, 0, v3, s[94:95]
	v_cndmask_b32_e64 v2, v5, v2, s[94:95]
	v_lshlrev_b64 v[130:131], 11, v[2:3]
	v_sub_u32_e32 v2, v219, v10
	v_cmp_gt_i32_e64 s[96:97], s33, v2
	v_ashrrev_i32_e32 v3, 31, v2
	v_add_u32_e32 v5, 0xfffff800, v2
	v_cndmask_b32_e64 v3, 0, v3, s[96:97]
	v_cndmask_b32_e64 v2, v5, v2, s[96:97]
	v_lshlrev_b64 v[132:133], 11, v[2:3]
	v_sub_u32_e32 v2, v219, v11
	v_cmp_gt_i32_e64 s[72:73], s33, v2
	v_ashrrev_i32_e32 v3, 31, v2
	v_add_u32_e32 v5, 0xfffff800, v2
	v_cndmask_b32_e64 v3, 0, v3, s[72:73]
	v_cndmask_b32_e64 v2, v5, v2, s[72:73]
	v_lshlrev_b64 v[134:135], 11, v[2:3]
	v_sub_u32_e32 v2, v219, v12
	v_cmp_gt_i32_e64 s[28:29], s33, v2
	v_ashrrev_i32_e32 v3, 31, v2
	v_add_u32_e32 v5, 0xfffff800, v2
	v_cndmask_b32_e64 v3, 0, v3, s[28:29]
	v_cndmask_b32_e64 v2, v5, v2, s[28:29]
	v_lshlrev_b64 v[136:137], 11, v[2:3]
	v_sub_u32_e32 v2, v219, v13
	v_cmp_gt_i32_e64 s[30:31], s33, v2
	v_ashrrev_i32_e32 v3, 31, v2
	v_add_u32_e32 v5, 0xfffff800, v2
	v_cndmask_b32_e64 v3, 0, v3, s[30:31]
	v_cndmask_b32_e64 v2, v5, v2, s[30:31]
	v_lshlrev_b64 v[138:139], 11, v[2:3]
	v_sub_u32_e32 v2, v219, v14
	v_cmp_gt_i32_e64 s[34:35], s33, v2
	v_ashrrev_i32_e32 v3, 31, v2
	v_add_u32_e32 v5, 0xfffff800, v2
	v_cndmask_b32_e64 v3, 0, v3, s[34:35]
	v_cndmask_b32_e64 v2, v5, v2, s[34:35]
	v_lshlrev_b64 v[140:141], 11, v[2:3]
	v_sub_u32_e32 v2, v219, v15
	v_cmp_gt_i32_e64 s[40:41], s33, v2
	v_ashrrev_i32_e32 v3, 31, v2
	v_add_u32_e32 v5, 0xfffff800, v2
	v_or_b32_e32 v16, 48, v193
	v_cndmask_b32_e64 v3, 0, v3, s[40:41]
	v_cndmask_b32_e64 v2, v5, v2, s[40:41]
	v_lshlrev_b64 v[142:143], 11, v[2:3]
	v_sub_u32_e32 v2, v219, v16
	v_cmp_gt_i32_e64 s[42:43], s33, v2
	v_ashrrev_i32_e32 v3, 31, v2
	v_add_u32_e32 v5, 0xfffff800, v2
	v_or_b32_e32 v17, 52, v193
	v_cndmask_b32_e64 v3, 0, v3, s[42:43]
	v_cndmask_b32_e64 v2, v5, v2, s[42:43]
	v_lshlrev_b64 v[144:145], 11, v[2:3]
	v_sub_u32_e32 v2, v219, v17
	v_cmp_gt_i32_e64 s[44:45], s33, v2
	v_ashrrev_i32_e32 v3, 31, v2
	v_add_u32_e32 v5, 0xfffff800, v2
	v_or_b32_e32 v18, 56, v193
	v_cndmask_b32_e64 v3, 0, v3, s[44:45]
	v_cndmask_b32_e64 v2, v5, v2, s[44:45]
	v_lshlrev_b64 v[146:147], 11, v[2:3]
	v_sub_u32_e32 v2, v219, v18
	v_cmp_gt_i32_e64 s[50:51], s33, v2
	v_ashrrev_i32_e32 v3, 31, v2
	v_add_u32_e32 v5, 0xfffff800, v2
	v_or_b32_e32 v19, 60, v193
	v_cndmask_b32_e64 v3, 0, v3, s[50:51]
	v_cndmask_b32_e64 v2, v5, v2, s[50:51]
	v_lshlrev_b64 v[148:149], 11, v[2:3]
	v_sub_u32_e32 v2, v219, v19
	v_cmp_gt_i32_e64 s[74:75], s33, v2
	v_ashrrev_i32_e32 v3, 31, v2
	v_add_u32_e32 v5, 0xfffff800, v2
	v_or_b32_e32 v20, 64, v193
	v_cndmask_b32_e64 v3, 0, v3, s[74:75]
	v_cndmask_b32_e64 v2, v5, v2, s[74:75]
	v_lshlrev_b64 v[150:151], 11, v[2:3]
	v_sub_u32_e32 v2, v219, v20
	v_lshl_add_u64 v[108:109], s[80:81], 0, v[104:105]
	v_cmp_gt_i32_e64 s[80:81], s33, v2
	v_ashrrev_i32_e32 v3, 31, v2
	v_add_u32_e32 v5, 0xfffff800, v2
	v_or_b32_e32 v21, 0x44, v193
	v_cndmask_b32_e64 v3, 0, v3, s[80:81]
	v_cndmask_b32_e64 v2, v5, v2, s[80:81]
	v_lshlrev_b64 v[152:153], 11, v[2:3]
	v_sub_u32_e32 v2, v219, v21
	v_cmp_gt_i32_e64 s[88:89], s33, v2
	v_ashrrev_i32_e32 v3, 31, v2
	v_add_u32_e32 v5, 0xfffff800, v2
	v_or_b32_e32 v22, 0x48, v193
	v_cndmask_b32_e64 v3, 0, v3, s[88:89]
	v_cndmask_b32_e64 v2, v5, v2, s[88:89]
	v_lshlrev_b64 v[154:155], 11, v[2:3]
	v_sub_u32_e32 v2, v219, v22
	v_cmp_gt_i32_e64 s[90:91], s33, v2
	v_ashrrev_i32_e32 v3, 31, v2
	v_add_u32_e32 v5, 0xfffff800, v2
	v_or_b32_e32 v23, 0x4c, v193
	v_cndmask_b32_e64 v3, 0, v3, s[90:91]
	v_cndmask_b32_e64 v2, v5, v2, s[90:91]
	v_lshlrev_b64 v[156:157], 11, v[2:3]
	v_sub_u32_e32 v2, v219, v23
	v_cmp_gt_i32_e64 s[52:53], s33, v2
	v_ashrrev_i32_e32 v3, 31, v2
	v_add_u32_e32 v5, 0xfffff800, v2
	v_or_b32_e32 v24, 0x50, v193
	v_cndmask_b32_e64 v3, 0, v3, s[52:53]
	v_cndmask_b32_e64 v2, v5, v2, s[52:53]
	v_lshlrev_b64 v[158:159], 11, v[2:3]
	v_sub_u32_e32 v2, v219, v24
	v_cmp_gt_i32_e64 s[54:55], s33, v2
	v_ashrrev_i32_e32 v3, 31, v2
	v_add_u32_e32 v5, 0xfffff800, v2
	v_or_b32_e32 v220, 0x54, v193
	v_cndmask_b32_e64 v3, 0, v3, s[54:55]
	v_cndmask_b32_e64 v2, v5, v2, s[54:55]
	v_lshlrev_b64 v[160:161], 11, v[2:3]
	v_sub_u32_e32 v2, v219, v220
	v_cmp_gt_i32_e64 s[56:57], s33, v2
	v_ashrrev_i32_e32 v3, 31, v2
	v_add_u32_e32 v5, 0xfffff800, v2
	v_or_b32_e32 v25, 0x58, v193
	v_cndmask_b32_e64 v3, 0, v3, s[56:57]
	v_cndmask_b32_e64 v2, v5, v2, s[56:57]
	v_writelane_b32 v247, s1, 41
	v_lshlrev_b64 v[162:163], 11, v[2:3]
	v_sub_u32_e32 v2, v219, v25
	v_cmp_gt_u32_e64 s[0:1], 16, v100
	v_cmp_gt_i32_e64 s[58:59], s33, v2
	v_ashrrev_i32_e32 v3, 31, v2
	v_add_u32_e32 v5, 0xfffff800, v2
	v_writelane_b32 v247, s0, 42
	v_add_u32_e32 v4, 1, v101
	v_or_b32_e32 v26, 0x5c, v193
	v_cndmask_b32_e64 v3, 0, v3, s[58:59]
	v_cndmask_b32_e64 v2, v5, v2, s[58:59]
	v_writelane_b32 v247, s1, 43
	v_cmp_lt_u32_e64 s[0:1], 6, v101
	v_lshlrev_b64 v[164:165], 11, v[2:3]
	v_sub_u32_e32 v2, v219, v26
	v_and_b32_e32 v224, 7, v4
	v_writelane_b32 v247, s0, 44
	v_cmp_gt_i32_e64 s[60:61], s33, v2
	v_ashrrev_i32_e32 v3, 31, v2
	v_add_u32_e32 v5, 0xfffff800, v2
	v_writelane_b32 v247, s1, 45
	v_cmp_ne_u32_e64 s[0:1], 0, v224
	v_or_b32_e32 v27, 0x60, v193
	v_cndmask_b32_e64 v3, 0, v3, s[60:61]
	v_cndmask_b32_e64 v2, v5, v2, s[60:61]
	v_writelane_b32 v247, s0, 46
	v_sub_u32_e32 v1, v112, v0
	v_lshlrev_b64 v[166:167], 11, v[2:3]
	v_sub_u32_e32 v2, v219, v27
	v_writelane_b32 v247, s1, 47
	v_lshl_add_u32 v0, v0, 8, 0
	s_movk_i32 s0, 0x700
	v_cvt_f32_i32_e32 v117, v1
	v_cvt_f32_i32_e32 v212, v4
	v_cmp_gt_i32_e64 s[62:63], s33, v2
	v_ashrrev_i32_e32 v3, 31, v2
	v_add_u32_e32 v5, 0xfffff800, v2
	v_add_u32_e32 v229, 0x800, v0
	v_mul_lo_u32 v0, v101, s0
	v_cndmask_b32_e64 v3, 0, v3, s[62:63]
	v_cndmask_b32_e64 v2, v5, v2, s[62:63]
	v_lshl_or_b32 v0, v193, 2, v0
	v_add_u32_e32 v102, 0x4000, v101
	v_add_u32_e32 v210, 0, v104
	v_lshlrev_b32_e32 v1, 11, v101
	v_lshlrev_b32_e32 v116, 2, v189
	v_lshlrev_b64 v[168:169], 11, v[2:3]
	v_or_b32_e32 v2, 0x180, v100
	s_movk_i32 s14, 0x183
	v_add_u32_e32 v0, 0, v0
	s_mov_b32 s5, 0
	v_lshl_add_u32 v113, v209, 2, 0
	v_ashrrev_i32_e32 v103, 31, v102
	v_cmp_eq_u32_e64 s[10:11], 0, v189
	v_add_u32_e32 v221, v118, v104
	v_cmp_gt_u32_e64 s[64:65], s14, v2
	v_and_b32_e32 v225, 0x7ffffff8, v4
	v_sub_u32_e32 v226, 0x183, v25
	v_sub_u32_e32 v227, 0x183, v26
	v_sub_u32_e32 v228, 0x183, v27
	v_add_u32_e32 v230, 0x2000, v114
	v_add_u32_e32 v231, 0x1000, v210
	v_add_u32_e32 v232, 0x6100, v0
	s_movk_i32 s15, 0x80
	v_or_b32_e32 v233, 0x80, v193
	v_sub_u32_e32 v234, 0xffffffb0, v193
	v_add_u32_e32 v235, 0x6110, v0
	s_movk_i32 s92, 0x1c00
	v_add_u32_e32 v236, v210, v1
	v_mov_b32_e32 v237, 0x358637bd
	v_lshlrev_b32_e32 v170, 2, v116
	s_movk_i32 s16, 0x102
	s_movk_i32 s17, 0x81
	v_mov_b32_e32 v238, 0x41b17218
	v_mov_b32_e32 v239, 0x182
	v_readlane_b32 s8, v247, 23
	v_readlane_b32 s9, v247, 24
	s_branch .LBB0_292

.LBB0_394:
	s_setprio 0
	s_cmp_eq_u32 s100, 2
	s_cbranch_scc0 .Lstag_attn
	v_readlane_b32 s4, v252, 0
	v_readlane_b32 s5, v252, 1
	v_readlane_b32 s6, v252, 2
	v_readlane_b32 s7, v252, 3
	v_readlane_b32 s10, v252, 4
	v_readlane_b32 s11, v252, 5
	v_readlane_b32 s14, v252, 6
	v_readlane_b32 s15, v252, 7
	v_readlane_b32 s16, v252, 8
	v_readlane_b32 s17, v252, 9
	v_readlane_b32 s18, v252, 10
	v_readlane_b32 s19, v252, 11
	v_readlane_b32 s28, v252, 12
	v_readlane_b32 s29, v252, 13
	v_readlane_b32 s30, v252, 14
	v_readlane_b32 s31, v252, 15
	v_readlane_b32 s34, v252, 16
	v_readlane_b32 s35, v252, 17
	v_readlane_b32 s41, v252, 18
	v_readlane_b32 s43, v252, 19
	v_readlane_b32 s54, v252, 20
	v_readlane_b32 s55, v252, 21
	v_readlane_b32 s56, v252, 22
	v_readlane_b32 s57, v252, 23
	v_readlane_b32 s58, v252, 24
	v_readlane_b32 s88, v252, 25
	v_readlane_b32 s89, v252, 26
	v_readlane_b32 s90, v252, 27
	v_readlane_b32 s91, v252, 28
	v_readlane_b32 s96, v252, 29
	s_branch .Lstag_done
